# grid barrier: XCD leader bumps the per-XCD generation before its own L1 invalidate
# baseline (speedup 1.0000x reference)
.LBB0_9:
	s_or_b64 exec, exec, s[22:23]
	buffer_inv sc1
	s_waitcnt vmcnt(0)

.LBB0_185:
	s_or_b64 exec, exec, s[20:21]
	s_mov_b64 s[20:21], exec
	v_mbcnt_lo_u32_b32 v0, s20, 0
	v_mbcnt_hi_u32_b32 v0, s21, v0
	v_cmp_eq_u32_e32 vcc, 0, v0
	s_nop 0
	s_and_saveexec_b64 s[22:23], vcc
	s_cbranch_execz .LBB0_9
	s_bcnt1_i32_b64 s6, s[20:21]
	v_readlane_b32 s20, v254, 30
	v_mov_b32_e32 v0, s6
	v_readlane_b32 s21, v254, 31
	s_nop 4
	global_atomic_add v1, v0, s[20:21]
	s_branch .LBB0_9
